# conversion engine v6: item work spread over the 16 load-segment heads of its 4 iterations (decode split D1/D2/D3, one row group / 4 transposed reads per head)
# baseline (speedup 1.0000x reference)
.LBB0_137:
	s_lshl_b32 s5, s5, 5
	s_mov_b64 s[18:19], 0x80
	s_and_b32 s5, s5, 0x60
	s_add_i32 m0, s55, 0x18000
	v_lshl_add_u64 v[8:9], v[8:9], 0, s[18:19]
	s_lshl_b32 s1, s4, 13
	s_lshl_b32 s22, s5, 7
	s_waitcnt vmcnt(2)
	s_barrier
	global_load_lds_dwordx4 v[8:9], off
	v_lshl_add_u64 v[4:5], v[4:5], 0, s[18:19]
	s_add_i32 m0, s55, 0x1a000
	s_add_i32 s75, s55, 0x8000
	s_add_i32 s76, s55, 0xa000
	global_load_lds_dwordx4 v[4:5], off
	v_lshl_add_u64 v[2:3], v[2:3], 0, s[18:19]
	s_mov_b32 m0, s75
	s_add_u32 s20, s8, 0x100080
	global_load_lds_dwordx4 v[2:3], off
	v_lshl_add_u64 v[2:3], v[6:7], 0, s[18:19]
	s_mov_b32 m0, s76
	s_addc_u32 s21, s9, 0
	global_load_lds_dwordx4 v[2:3], off
	s_add_i32 m0, s55, 0x1c000
	v_lshl_add_u64 v[2:3], s[20:21], 0, v[140:141]
	global_load_lds_dwordx4 v[2:3], off
	v_lshl_add_u64 v[2:3], s[20:21], 0, v[144:145]
	s_add_i32 m0, s55, 0x1e000
	v_and_b32_e32 v4, 32, v162
	global_load_lds_dwordx4 v[2:3], off
	v_and_b32_e32 v2, 15, v0
	v_lshlrev_b32_e32 v3, 1, v14
	v_lshl_or_b32 v163, s4, 6, v2
	v_lshl_or_b32 v2, v2, 6, v3
	v_bitop3_b32 v2, v2, s1, v4 bitop3:0xde
	v_lshlrev_b32_e32 v5, 6, v0
	s_movk_i32 s1, 0x3c0
	v_and_or_b32 v3, v5, s1, v3
	v_bitop3_b32 v164, s22, v3, v4 bitop3:0xf6
	v_lshlrev_b32_e32 v3, 10, v0
	v_and_b32_e32 v3, 0x60000, v3
	v_lshlrev_b32_e32 v4, 13, v12
	v_or3_b32 v3, v10, v3, v4
	s_cmpk_lt_u32 s14, 0x100
	v_add_u32_e32 v148, v3, v11
	v_lshlrev_b32_e32 v3, 6, v13
	s_waitcnt vmcnt(6)
	s_cselect_b64 s[20:21], -1, 0
	s_add_u32 s22, s62, 0x2000
	v_and_b32_e32 v3, 0xe0000, v3
	v_or_b32_e32 v165, s5, v14
	s_addc_u32 s23, s63, 0
	v_or3_b32 v3, v10, v3, v4
	s_add_i32 s83, 0, 0x10000
	s_add_i32 s89, 0, 0x14000
	v_or_b32_e32 v166, 0xffffec00, v165
	s_ashr_i32 s77, s74, 31
	s_ashr_i32 s81, s2, 31
	v_mov_b32_e32 v149, v147
	v_add_u32_e32 v150, v3, v11
	v_mov_b32_e32 v151, v147
	v_mov_b64_e32 v[152:153], 0x900
	v_mov_b64_e32 v[154:155], 0x8ff
	v_add_u32_e32 v167, s83, v164
	v_add_u32_e32 v168, s89, v164
	v_add_u32_e32 v169, 0, v2
	s_mov_b32 s90, 0xc2a00000
	s_mov_b32 s91, 0xc1f00000
	v_mov_b32_e32 v170, 0x42a00000
	v_mov_b32_e32 v171, 0x41f00000
	s_mov_b32 s92, 0
	s_barrier
	s_bfe_u32 s32, s2, 0x20003
	s_sub_i32 s32, 0, s32
	s_mov_b32 s97, 0
	v_readlane_b32 s98, v244, 0
	v_readlane_b32 s99, v244, 1
	s_nop 3
	s_sub_u32 s98, s98, 0x98
	s_subb_u32 s99, s99, 0
	s_load_dwordx2 s[100:101], s[98:99], 0x58
	s_waitcnt lgkmcnt(0)
	v_writelane_b32 v245, s100, 0
	v_writelane_b32 v245, s101, 1
	s_nop 1
	s_load_dwordx2 s[100:101], s[98:99], 0x60
	s_waitcnt lgkmcnt(0)
	v_writelane_b32 v245, s100, 2
	v_writelane_b32 v245, s101, 3
	s_nop 1
	s_load_dwordx2 s[100:101], s[98:99], 0x50
	s_waitcnt lgkmcnt(0)
	v_writelane_b32 v245, s100, 4
	v_writelane_b32 v245, s101, 5
	s_nop 1
	s_load_dwordx2 s[100:101], s[98:99], 0x38
	s_waitcnt lgkmcnt(0)
	v_writelane_b32 v245, s100, 6
	v_writelane_b32 v245, s101, 7
	s_nop 1
	s_load_dwordx2 s[100:101], s[98:99], 0x40
	s_waitcnt lgkmcnt(0)
	v_writelane_b32 v245, s100, 8
	v_writelane_b32 v245, s101, 9
	s_nop 1
	s_load_dwordx2 s[100:101], s[98:99], 0x48
	s_waitcnt lgkmcnt(0)
	v_writelane_b32 v245, s100, 10
	v_writelane_b32 v245, s101, 11
	s_nop 1
	s_mul_hi_u32 s93, s80, 0xbe82fa0c
	s_lshr_b32 s93, s93, 8
	s_mul_i32 s85, s93, 0x158
	s_sub_i32 s85, s80, s85
	s_lshl_b32 s93, s93, 16
	s_or_b32 s85, s85, s93
	s_mov_b64 s[100:101], 0
	s_bitcmp1_b32 s85, 31
	s_cbranch_scc1 .LD2_B_i
	s_lshr_b32 s98, s85, 16
	s_and_b32 s99, s85, 0xffff
	s_lshr_b32 s100, s99, 2
	s_lshl_b32 s100, s100, 8
	s_and_b32 s99, s99, 3
	s_lshl_b32 s99, s99, 5
	s_add_i32 s100, s100, s99
	s_xor_b32 s99, s98, 0x80
	s_and_b32 s99, s99, 0x80
	s_add_i32 s100, s100, s99
	s_lshl_b32 s100, s100, 13
	s_and_b32 s98, s98, 0x7f
	s_lshl_b32 s98, s98, 6
	s_add_i32 s100, s100, s98
	v_readlane_b32 s98, v244, 6
	v_readlane_b32 s99, v244, 7
	s_nop 3
	s_add_u32 s100, s98, s100
	s_addc_u32 s101, s99, 0
	s_branch .LD2_done_i
.LD2_B_i:
	s_and_b32 s98, s85, 0x7fffffff
	s_cmp_ge_u32 s98, 0x8000
	s_cbranch_scc1 .LD2_done_i
	s_lshr_b32 s99, s98, 13
	s_cmp_ge_u32 s99, 2
	s_cbranch_scc1 .LD2_B2_i
	v_readlane_b32 s100, v244, 2
	v_readlane_b32 s101, v244, 3
	s_lshl_b32 s99, s99, 12
	s_and_b32 s98, s98, 0x1fff
	s_branch .LD2_Bm_i
.LD2_B2_i:
	v_readlane_b32 s100, v244, 4
	v_readlane_b32 s101, v244, 5
	s_mov_b32 s99, 0
	s_and_b32 s98, s98, 0x3fff
	s_nop 0
.LD2_Bm_i:
	s_nop 1
	s_add_u32 s100, s100, s99
	s_addc_u32 s101, s101, 0
	s_lshr_b32 s99, s98, 7
	s_lshl_b32 s99, s99, 6
	s_add_u32 s100, s100, s99
	s_addc_u32 s101, s101, 0
	s_and_b32 s98, s98, 0x7f
	s_lshl_b32 s98, s98, 18
	s_add_u32 s100, s100, s98
	s_addc_u32 s101, s101, 0
	s_or_b32 s100, s100, 1
.LD2_done_i:
	s_cmp_eq_u64 s[100:101], 0
	s_cbranch_scc1 .LD3_done_i
	s_bitcmp1_b32 s85, 31
	s_cbranch_scc1 .LD3_B_i
	s_lshr_b32 s93, s85, 16
	s_cmp_lt_u32 s93, 0x80
	s_cbranch_scc0 .LD3_gate_i
	v_readlane_b32 s98, v245, 2
	v_readlane_b32 s99, v245, 3
	s_branch .LD3_Am_i
.LD3_gate_i:
	v_readlane_b32 s98, v245, 0
	v_readlane_b32 s99, v245, 1
	s_nop 0
.LD3_Am_i:
	s_and_b32 s93, s93, 0x7f
	s_mul_i32 s97, s93, 0x158000
	s_lshl_b32 s93, s93, 7
	v_writelane_b32 v245, s93, 12
	s_add_u32 s98, s98, s97
	s_addc_u32 s99, s99, 0
	s_and_b32 s97, s85, 0xffff
	s_lshl_b32 s97, s97, 7
	s_add_u32 s98, s98, s97
	s_addc_u32 s99, s99, 0
	s_branch .LD3_done_i
.LD3_B_i:
	s_and_b32 s93, s85, 0x7fffffff
	s_lshr_b32 s97, s93, 13
	s_cmp_eq_u32 s97, 0
	s_cbranch_scc0 .LD3_B1_i
	v_readlane_b32 s98, v245, 6
	v_readlane_b32 s99, v245, 7
	s_and_b32 s93, s93, 0x1fff
	s_branch .LD3_Bm_i
.LD3_B1_i:
	s_cmp_eq_u32 s97, 1
	s_cbranch_scc0 .LD3_B2_i
	v_readlane_b32 s98, v245, 8
	v_readlane_b32 s99, v245, 9
	s_and_b32 s93, s93, 0x1fff
	s_branch .LD3_Bm_i
.LD3_B2_i:
	v_readlane_b32 s98, v245, 10
	v_readlane_b32 s99, v245, 11
	s_and_b32 s93, s93, 0x3fff
	s_nop 0
.LD3_Bm_i:
	s_lshr_b32 s97, s93, 7
	s_lshl_b32 s97, s97, 19
	s_add_u32 s98, s98, s97
	s_addc_u32 s99, s99, 0
	s_and_b32 s93, s93, 0x7f
	s_lshl_b32 s93, s93, 7
	s_add_u32 s98, s98, s93
	s_addc_u32 s99, s99, 0
.LD3_done_i:
	s_branch .LBB0_140
.LBB0_138:
	s_mov_b64 s[0:1], 0

; __device__ __forceinline__ unsigned cvt_pk_bf16(float lo, float hi) { const cvt_f2 v = {lo, hi}; return __builtin_bit_cast(unsigned, __builtin_convertvector(v, cvt_b2)); }
; #define GAS __attribute__((address_space(1)))
; #define LAS __attribute__((address_space(3)))
; #define LDS_WAIT() asm volatile("s_waitcnt lgkmcnt(0)" ::: "memory")
; __device__ __forceinline__ void conv_load(const ConvItem& it, int lane, f32x4 (&v)[4]) {
;     const int lk = lane >> 3, ln = (lane & 7) * 4;
; #pragma unroll
;     for (int i = 0; i < 4; ++i) v[i] = __builtin_nontemporal_load((const GAS f32x4*)(it.W + (size_t)(it.k0 + 8 * i + lk) * it.N + it.n0 + ln));
; }
; __device__ __forceinline__ void conv_store(const ConvItem& it, int lane, const f32x4 (&v)[4], LAS bf16* scr) {
;     const int lk = lane >> 3, ln = (lane & 7) * 4;
; #pragma unroll
;     for (int i = 0; i < 4; ++i) { const float gk = it.kgain ? it.kgain[it.k0 + 8 * i + lk] : 1.0f; LAS unsigned* p = (LAS unsigned*)(scr + (8 * i + lk) * 34 + ln); p[0] = pg8::cvt_pk_bf16(v[i][0] * gk, v[i][1] * gk); p[1] = pg8::cvt_pk_bf16(v[i][2] * gk, v[i][3] * gk); }
;     LDS_WAIT(); asm volatile("" ::: "memory");
.LBB0_143:
	s_add_i32 s32, s32, 1
	s_mov_b32 s97, 0
	s_mov_b32 s93, 4
	s_cmp_lt_i32 s32, 1
	s_cbranch_scc1 .LS1_done
	s_sub_i32 s93, s32, 1
	s_and_b32 s93, s93, 3
	s_cmp_eq_u64 s[100:101], 0
	s_cbranch_scc1 .LS1_done
	s_cmp_lg_u32 s93, 0
	s_cbranch_scc1 .LS1_n0
	v_lshrrev_b32_e32 v254, 3, v1
	v_and_b32_e32 v255, 7, v1
	s_bitcmp1_b32 s100, 0
	s_cbranch_scc1 .LS1_ldB
	v_mul_u32_u24_e32 v254, 0xac00, v254
	v_lshl_add_u32 v254, v255, 4, v254
	v_lshrrev_b32_e32 v255, 3, v1
	v_lshlrev_b32_e32 v255, 2, v255
	global_load_dwordx4 v[232:235], v254, s[98:99] nt
	s_add_u32 s98, s98, 0x56000
	s_addc_u32 s99, s99, 0
	global_load_dwordx4 v[236:239], v254, s[98:99] nt
	s_add_u32 s98, s98, 0x56000
	s_addc_u32 s99, s99, 0
	global_load_dwordx4 v[240:243], v254, s[98:99] nt
	s_add_u32 s98, s98, 0x56000
	s_addc_u32 s99, s99, 0
	global_load_dwordx4 v[246:249], v254, s[98:99] nt
	v_readlane_b32 s98, v245, 4
	v_readlane_b32 s99, v245, 5
	v_readlane_b32 s97, v245, 12
	s_nop 3
	s_add_u32 s98, s98, s97
	s_addc_u32 s99, s99, 0
	global_load_dword v250, v255, s[98:99]
	global_load_dword v251, v255, s[98:99] offset:32
	global_load_dword v252, v255, s[98:99] offset:64
	global_load_dword v253, v255, s[98:99] offset:96
	s_mov_b32 s97, 8
	s_branch .LS1_done
.LS1_ldB:
	v_lshlrev_b32_e32 v254, 14, v254
	v_lshl_add_u32 v254, v255, 4, v254
	v_mov_b32_e32 v250, 1.0
	v_mov_b32_e32 v251, 1.0
	global_load_dwordx4 v[232:235], v254, s[98:99] nt
	s_add_u32 s98, s98, 0x20000
	s_addc_u32 s99, s99, 0
	global_load_dwordx4 v[236:239], v254, s[98:99] nt
	s_add_u32 s98, s98, 0x20000
	s_addc_u32 s99, s99, 0
	global_load_dwordx4 v[240:243], v254, s[98:99] nt
	s_add_u32 s98, s98, 0x20000
	s_addc_u32 s99, s99, 0
	global_load_dwordx4 v[246:249], v254, s[98:99] nt
	v_mov_b32_e32 v252, 1.0
	v_mov_b32_e32 v253, 1.0
	s_mov_b32 s97, 4
	s_branch .LS1_done
.LS1_n0:
	s_cmp_lg_u32 s93, 1
	s_cbranch_scc1 .LS1_n1
	v_readlane_b32 s98, v244, 10
	v_lshrrev_b32_e32 v254, 3, v1
	v_mul_u32_u24_e32 v254, 0x44, v254
	v_and_b32_e32 v255, 7, v1
	v_lshl_add_u32 v254, v255, 3, v254
	s_mulk_i32 s98, 0x900
	s_add_i32 s98, s98, 0x22400
	v_add_u32_e32 v254, s98, v254
	v_add_u32_e32 v255, 0x440, v254
	v_mul_f32_e32 v232, v250, v232
	v_mul_f32_e32 v233, v250, v233
	v_mul_f32_e32 v234, v250, v234
	v_mul_f32_e32 v235, v250, v235
	v_cvt_pk_bf16_f32 v232, v232, v233
	v_cvt_pk_bf16_f32 v233, v234, v235
	ds_write2_b32 v254, v232, v233 offset1:1
	s_branch .LS1_done
.LS1_n1:
	s_cmp_lg_u32 s93, 2
	s_cbranch_scc1 .LS1_n2
	v_readlane_b32 s98, v244, 10
	v_and_b32_e32 v254, 3, v1
	v_mul_u32_u24_e32 v254, 0x220, v254
	v_lshrrev_b32_e32 v255, 2, v1
	v_lshl_add_u32 v254, v255, 1, v254
	s_mulk_i32 s98, 0x900
	s_add_i32 s98, s98, 0x22400
	v_add_u32_e32 v254, s98, v254
	ds_read_u16 v232, v254
	ds_read_u16 v233, v254 offset:68
	ds_read_u16 v234, v254 offset:136
	ds_read_u16 v235, v254 offset:204
	s_branch .LS1_done
.LS1_n2:
	v_and_b32_e32 v254, 3, v1
	v_lshlrev_b32_e32 v254, 4, v254
	v_lshrrev_b32_e32 v255, 2, v1
	v_lshl_add_u32 v254, v255, 13, v254
	v_add_u32_e32 v255, 0x20000, v254
	v_lshl_or_b32 v232, v233, 16, v232
	v_lshl_or_b32 v233, v235, 16, v234
	v_lshl_or_b32 v234, v237, 16, v236
	v_lshl_or_b32 v235, v239, 16, v238
	v_lshl_or_b32 v236, v241, 16, v240
	v_lshl_or_b32 v237, v243, 16, v242
	v_lshl_or_b32 v238, v247, 16, v246
	v_lshl_or_b32 v239, v249, 16, v248
	s_and_b32 s98, s100, -2
	s_mov_b32 s99, s101
	global_store_dwordx4 v254, v[232:235], s[98:99] nt
	global_store_dwordx4 v255, v[236:239], s[98:99] nt
	s_mov_b32 s97, 2
.LS1_done:
	ds_read_b128 v[130:133], v167
	ds_read_b128 v[134:137], v167 offset:1024
	ds_read_b128 v[156:159], v167 offset:2048
	ds_read_b128 v[172:175], v167 offset:3072
	ds_read_b128 v[176:179], v168
	ds_read_b128 v[180:183], v168 offset:1024
	ds_read_b128 v[184:187], v168 offset:2048
	ds_read_b128 v[188:191], v168 offset:3072
	s_add_u32 s8, s6, 0xfff00080
	s_addc_u32 s9, s7, -1
	s_cmp_eq_u32 s45, 60
	s_cselect_b32 s37, s1, s9
	s_cselect_b32 s36, s14, s8
	s_cselect_b32 s9, s25, s44
	s_cselect_b32 s8, s27, s33
	v_lshl_add_u64 v[160:161], s[6:7], 0, v[148:149]
	s_add_i32 m0, s55, 0xc000
	ds_read_b128 v[192:195], v169
	ds_read_b128 v[196:199], v169 offset:1024
	ds_read_b128 v[200:203], v169 offset:2048
	ds_read_b128 v[204:207], v169 offset:3072
	ds_read_b128 v[208:211], v169 offset:4096
	ds_read_b128 v[212:215], v169 offset:5120
	ds_read_b128 v[216:219], v169 offset:6144
	ds_read_b128 v[220:223], v169 offset:7168
	global_load_lds_dwordx4 v[160:161], off
	v_lshl_add_u64 v[160:161], s[6:7], 0, v[150:151]
	s_add_i32 m0, s55, 0xe000
	s_nop 0
	global_load_lds_dwordx4 v[160:161], off
	s_cmp_eq_u32 s97, 0
	s_cbranch_scc1 .Lengw1_a
	s_cmp_eq_u32 s97, 2
	s_cbranch_scc1 .Lengw1_b
	s_cmp_eq_u32 s97, 4
	s_cbranch_scc1 .Lengw1_c
	s_waitcnt vmcnt(16)
	s_branch .Lengw1_e

; #define PG8_STAGE(bufoff, gbase, voff) do { _Pragma("unroll") for (int _i = 0; _i < 2; ++_i) \
;         __builtin_amdgcn_global_load_lds((const unsigned*)((const char*)(gbase) + (voff)[_i]), (PG8_LAS unsigned*)(lds + (bufoff) + ldsw + _i * 8192), 16, 0, 0); } while (0)
; #define PG8_LDA(dst, b, h) do { _Pragma("unroll") for (int m = 0; m < 4; ++m) _Pragma("unroll") for (int k = 0; k < 2; ++k) dst[m][k] = *(const PG8_LAS bf16x8*)(lds + PG8_SA(b, h) + aoff + m * 2048 + k * 1024); } while (0)
; #define PG8_MMA(ai, bj, At, Bt) do { __builtin_amdgcn_s_setprio(3); _Pragma("unroll") for (int m = 0; m < 4; ++m) _Pragma("unroll") for (int n = 0; n < 2; ++n) _Pragma("unroll") for (int k = 0; k < 2; ++k) \
;         acc[ai][bj][m][n] = __builtin_amdgcn_mfma_f32_16x16x32_bf16(Bt[n][k], At[m][k], acc[ai][bj][m][n], 0, 0, 0); __builtin_amdgcn_s_setprio(0); } while (0)
; #define PG8_WAIT_V(n) asm volatile("s_waitcnt vmcnt(" #n ")" ::: "memory")
; #define PG8_WAIT_L(n) asm volatile("s_waitcnt lgkmcnt(" #n ")" ::: "memory")
; #define PG8_BAR __builtin_amdgcn_s_barrier()
; #define PG8_SCHED __builtin_amdgcn_sched_barrier(0)
; template <class Epi, class Sched, bool ALIGN_EPI = false, bool SP2 = false>
; __device__ __forceinline__ void gemm_phase(PG8_LAS unsigned char* lds, const Gemm g, const Sched& S, const Epi& E) {
;     ...
;             PG8_WAIT_V(8); PG8_WAIT_L(0); PG8_BAR; PG8_MMA(0, 0, At, B0); PG8_MMA(0, 1, At, B1); PG8_BAR; PG8_SCHED;
;             PG8_LDA(At, 0, 1); PG8_STAGE(PG8_SB(0, 0), b2, voffB); PG8_STAGE(PG8_SB(0, 1), b2 + hstepB, voffB); PG8_STAGE(PG8_SA(0, 0), a2, voffA);
.Lengw1_e:
	s_waitcnt lgkmcnt(0)
	s_barrier
	s_setprio 3
	s_waitcnt lgkmcnt(0)
	v_mfma_f32_16x16x32_bf16 v[126:129], v[130:133], v[192:195], v[126:129]
	v_mfma_f32_16x16x32_bf16 v[118:121], v[156:159], v[192:195], v[118:121]
	v_mfma_f32_16x16x32_bf16 v[110:113], v[130:133], v[200:203], v[110:113]
	v_mfma_f32_16x16x32_bf16 v[102:105], v[156:159], v[200:203], v[102:105]
	v_mfma_f32_16x16x32_bf16 v[94:97], v[130:133], v[208:211], v[94:97]
	v_mfma_f32_16x16x32_bf16 v[86:89], v[156:159], v[208:211], v[86:89]
	v_mfma_f32_16x16x32_bf16 v[78:81], v[130:133], v[216:219], v[78:81]
	v_mfma_f32_16x16x32_bf16 v[70:73], v[156:159], v[216:219], v[70:73]
	v_mfma_f32_16x16x32_bf16 v[126:129], v[134:137], v[196:199], v[126:129]
	v_mfma_f32_16x16x32_bf16 v[118:121], v[172:175], v[196:199], v[118:121]
	v_mfma_f32_16x16x32_bf16 v[110:113], v[134:137], v[204:207], v[110:113]
	v_mfma_f32_16x16x32_bf16 v[102:105], v[172:175], v[204:207], v[102:105]
	v_mfma_f32_16x16x32_bf16 v[94:97], v[134:137], v[212:215], v[94:97]
	v_mfma_f32_16x16x32_bf16 v[86:89], v[172:175], v[212:215], v[86:89]
	v_mfma_f32_16x16x32_bf16 v[78:81], v[134:137], v[220:223], v[78:81]
	v_mfma_f32_16x16x32_bf16 v[70:73], v[172:175], v[220:223], v[70:73]
	s_setprio 0
	s_setprio 3
	v_mfma_f32_16x16x32_bf16 v[122:125], v[176:179], v[192:195], v[122:125]
	v_mfma_f32_16x16x32_bf16 v[114:117], v[184:187], v[192:195], v[114:117]
	v_mfma_f32_16x16x32_bf16 v[106:109], v[176:179], v[200:203], v[106:109]
	v_mfma_f32_16x16x32_bf16 v[98:101], v[184:187], v[200:203], v[98:101]
	v_mfma_f32_16x16x32_bf16 v[90:93], v[176:179], v[208:211], v[90:93]
	v_mfma_f32_16x16x32_bf16 v[82:85], v[184:187], v[208:211], v[82:85]
	v_mfma_f32_16x16x32_bf16 v[74:77], v[176:179], v[216:219], v[74:77]
	v_mfma_f32_16x16x32_bf16 v[66:69], v[184:187], v[216:219], v[66:69]
	v_mfma_f32_16x16x32_bf16 v[122:125], v[180:183], v[196:199], v[122:125]
	v_mfma_f32_16x16x32_bf16 v[114:117], v[188:191], v[196:199], v[114:117]
	v_mfma_f32_16x16x32_bf16 v[106:109], v[180:183], v[204:207], v[106:109]
	v_mfma_f32_16x16x32_bf16 v[98:101], v[188:191], v[204:207], v[98:101]
	v_mfma_f32_16x16x32_bf16 v[90:93], v[180:183], v[212:215], v[90:93]
	v_mfma_f32_16x16x32_bf16 v[82:85], v[188:191], v[212:215], v[82:85]
	v_mfma_f32_16x16x32_bf16 v[74:77], v[180:183], v[220:223], v[74:77]
	v_mfma_f32_16x16x32_bf16 v[66:69], v[188:191], v[220:223], v[66:69]
	s_setprio 0
	s_barrier
	s_cmp_lg_u32 s93, 3
	s_cbranch_scc1 .LS2_n3
	s_bitcmp1_b32 s85, 31
	s_cbranch_scc1 .LD1_B_s
	s_add_i32 s85, s85, 0x50148
	s_and_b32 s98, s85, 0xffff
	s_cmp_ge_u32 s98, 0x158
	s_cbranch_scc0 .LD1_A2_s
	s_add_i32 s85, s85, 0xfea8
.LD1_A2_s:
	s_lshr_b32 s98, s85, 16
	s_cmp_ge_u32 s98, 0x100
	s_cbranch_scc0 .LD1_done_s
	s_or_b32 s85, s80, 0x80000000
	s_branch .LD1_done_s
.LD1_B_s:
	s_add_i32 s85, s85, 0x800

; __device__ __forceinline__ unsigned cvt_pk_bf16(float lo, float hi) { const cvt_f2 v = {lo, hi}; return __builtin_bit_cast(unsigned, __builtin_convertvector(v, cvt_b2)); }
; #define PG8_STAGE(bufoff, gbase, voff) do { _Pragma("unroll") for (int _i = 0; _i < 2; ++_i) \
;         __builtin_amdgcn_global_load_lds((const unsigned*)((const char*)(gbase) + (voff)[_i]), (PG8_LAS unsigned*)(lds + (bufoff) + ldsw + _i * 8192), 16, 0, 0); } while (0)
; #define PG8_LDA(dst, b, h) do { _Pragma("unroll") for (int m = 0; m < 4; ++m) _Pragma("unroll") for (int k = 0; k < 2; ++k) dst[m][k] = *(const PG8_LAS bf16x8*)(lds + PG8_SA(b, h) + aoff + m * 2048 + k * 1024); } while (0)
; #define LAS __attribute__((address_space(3)))
; #define LDS_WAIT() asm volatile("s_waitcnt lgkmcnt(0)" ::: "memory")
; template <class Epi, class Sched, bool ALIGN_EPI = false, bool SP2 = false>
; __device__ __forceinline__ void gemm_phase(PG8_LAS unsigned char* lds, const Gemm g, const Sched& S, const Epi& E) {
;     ...
;             PG8_LDA(At, 0, 1); PG8_STAGE(PG8_SB(0, 0), b2, voffB); PG8_STAGE(PG8_SB(0, 1), b2 + hstepB, voffB); PG8_STAGE(PG8_SA(0, 0), a2, voffA);
; __device__ __forceinline__ void conv_store(const ConvItem& it, int lane, const f32x4 (&v)[4], LAS bf16* scr) {
;     ...
;     for (int i = 0; i < 4; ++i) { const float gk = it.kgain ? it.kgain[it.k0 + 8 * i + lk] : 1.0f; LAS unsigned* p = (LAS unsigned*)(scr + (8 * i + lk) * 34 + ln); p[0] = pg8::cvt_pk_bf16(v[i][0] * gk, v[i][1] * gk); p[1] = pg8::cvt_pk_bf16(v[i][2] * gk, v[i][3] * gk); }
;     LDS_WAIT(); asm volatile("" ::: "memory");
;     const int c = lane & 3;
; #pragma unroll
;     for (int j = 0; j < 2; ++j) { const int n = (lane >> 2) + 16 * j; const LAS bf16* sp = scr + (8 * c) * 34 + n;
;         v4u o; o.x = (unsigned)sp[0] | ((unsigned)sp[34] << 16); o.y = (unsigned)sp[68] | ((unsigned)sp[102] << 16); o.z = (unsigned)sp[136] | ((unsigned)sp[170] << 16); o.w = (unsigned)sp[204] | ((unsigned)sp[238] << 16);
.LS2_n3:
	s_cmp_eq_u64 s[100:101], 0
	s_cbranch_scc1 .LS2_done
	s_cmp_lg_u32 s93, 1
	s_cbranch_scc1 .LS2_n1
	v_mul_f32_e32 v236, v251, v236
	v_mul_f32_e32 v237, v251, v237
	v_mul_f32_e32 v238, v251, v238
	v_mul_f32_e32 v239, v251, v239
	v_cvt_pk_bf16_f32 v236, v236, v237
	v_cvt_pk_bf16_f32 v237, v238, v239
	ds_write2_b32 v254, v236, v237 offset0:136 offset1:137
	s_branch .LS2_done
.LS2_n1:
	s_cmp_lg_u32 s93, 2
	s_cbranch_scc1 .LS2_done
	ds_read_u16 v236, v254 offset:272
	ds_read_u16 v237, v254 offset:340
	ds_read_u16 v238, v254 offset:408
	ds_read_u16 v239, v254 offset:476
.LS2_done:
	s_add_i32 s56, s83, s66
	v_lshl_add_u64 v[160:161], s[8:9], 0, v[140:141]
	s_mov_b32 m0, s56
	ds_read_b128 v[192:195], v169 offset:16384
	ds_read_b128 v[196:199], v169 offset:17408
	ds_read_b128 v[200:203], v169 offset:18432
	ds_read_b128 v[204:207], v169 offset:19456
	ds_read_b128 v[208:211], v169 offset:20480
	ds_read_b128 v[212:215], v169 offset:21504
	ds_read_b128 v[216:219], v169 offset:22528
	ds_read_b128 v[220:223], v169 offset:23552
	global_load_lds_dwordx4 v[160:161], off
	s_add_i32 m0, s56, 0x2000
	s_add_u32 s56, s8, 0x100000
	v_lshl_add_u64 v[224:225], s[8:9], 0, v[144:145]
	s_addc_u32 s57, s9, 0
	s_add_i32 s58, s89, s66
	global_load_lds_dwordx4 v[224:225], off
	v_lshl_add_u64 v[226:227], s[56:57], 0, v[140:141]
	s_mov_b32 m0, s58
	v_lshl_add_u64 v[228:229], s[36:37], 0, v[142:143]
	global_load_lds_dwordx4 v[226:227], off
	v_lshl_add_u64 v[226:227], s[56:57], 0, v[144:145]
	s_add_i32 m0, s58, 0x2000
	s_nop 0
	global_load_lds_dwordx4 v[226:227], off
	v_lshl_add_u64 v[226:227], s[36:37], 0, v[138:139]
	s_mov_b32 m0, s55
	s_nop 0
	global_load_lds_dwordx4 v[226:227], off
	s_mov_b32 m0, s67
	s_nop 0
	global_load_lds_dwordx4 v[228:229], off
	s_cmp_eq_u32 s97, 0
	s_cbranch_scc1 .Lengw2_a
	s_cmp_eq_u32 s97, 2
	s_cbranch_scc1 .Lengw2_b
	s_cmp_eq_u32 s97, 4
	s_cbranch_scc1 .Lengw2_c
	s_waitcnt vmcnt(16)
	s_branch .Lengw2_e

; #define PG8_MMA(ai, bj, At, Bt) do { __builtin_amdgcn_s_setprio(3); _Pragma("unroll") for (int m = 0; m < 4; ++m) _Pragma("unroll") for (int n = 0; n < 2; ++n) _Pragma("unroll") for (int k = 0; k < 2; ++k) \
;         acc[ai][bj][m][n] = __builtin_amdgcn_mfma_f32_16x16x32_bf16(Bt[n][k], At[m][k], acc[ai][bj][m][n], 0, 0, 0); __builtin_amdgcn_s_setprio(0); } while (0)
; #define PG8_WAIT_V(n) asm volatile("s_waitcnt vmcnt(" #n ")" ::: "memory")
; #define PG8_WAIT_L(n) asm volatile("s_waitcnt lgkmcnt(" #n ")" ::: "memory")
; #define PG8_BAR __builtin_amdgcn_s_barrier()
; #define PG8_SCHED __builtin_amdgcn_sched_barrier(0)
; template <class Epi, class Sched, bool ALIGN_EPI = false, bool SP2 = false>
; __device__ __forceinline__ void gemm_phase(PG8_LAS unsigned char* lds, const Gemm g, const Sched& S, const Epi& E) {
;     ...
;             PG8_WAIT_V(8); PG8_WAIT_L(0); PG8_BAR; PG8_MMA(1, 0, At, B0); PG8_MMA(1, 1, At, B1); PG8_BAR; PG8_SCHED;
.Lengw2_e:
	s_waitcnt lgkmcnt(0)
	s_barrier
	s_setprio 3
	s_waitcnt lgkmcnt(0)
	v_mfma_f32_16x16x32_bf16 v[62:65], v[130:133], v[192:195], v[62:65]
	v_mfma_f32_16x16x32_bf16 v[54:57], v[156:159], v[192:195], v[54:57]
	v_mfma_f32_16x16x32_bf16 v[46:49], v[130:133], v[200:203], v[46:49]
	v_mfma_f32_16x16x32_bf16 v[38:41], v[156:159], v[200:203], v[38:41]
	v_mfma_f32_16x16x32_bf16 v[30:33], v[130:133], v[208:211], v[30:33]
	v_mfma_f32_16x16x32_bf16 v[22:25], v[156:159], v[208:211], v[22:25]
	v_mfma_f32_16x16x32_bf16 v[14:17], v[130:133], v[216:219], v[14:17]
	v_mfma_f32_16x16x32_bf16 v[6:9], v[156:159], v[216:219], v[6:9]
	v_mfma_f32_16x16x32_bf16 v[62:65], v[134:137], v[196:199], v[62:65]
	v_mfma_f32_16x16x32_bf16 v[54:57], v[172:175], v[196:199], v[54:57]
	v_mfma_f32_16x16x32_bf16 v[46:49], v[134:137], v[204:207], v[46:49]
	v_mfma_f32_16x16x32_bf16 v[38:41], v[172:175], v[204:207], v[38:41]
	v_mfma_f32_16x16x32_bf16 v[30:33], v[134:137], v[212:215], v[30:33]
	v_mfma_f32_16x16x32_bf16 v[22:25], v[172:175], v[212:215], v[22:25]
	v_mfma_f32_16x16x32_bf16 v[14:17], v[134:137], v[220:223], v[14:17]
	v_mfma_f32_16x16x32_bf16 v[6:9], v[172:175], v[220:223], v[6:9]
	s_setprio 0
	s_setprio 3
	v_mfma_f32_16x16x32_bf16 v[58:61], v[176:179], v[192:195], v[58:61]
	v_mfma_f32_16x16x32_bf16 v[50:53], v[184:187], v[192:195], v[50:53]
	v_mfma_f32_16x16x32_bf16 v[42:45], v[176:179], v[200:203], v[42:45]
	v_mfma_f32_16x16x32_bf16 v[34:37], v[184:187], v[200:203], v[34:37]
	v_mfma_f32_16x16x32_bf16 v[26:29], v[176:179], v[208:211], v[26:29]
	v_mfma_f32_16x16x32_bf16 v[18:21], v[184:187], v[208:211], v[18:21]
	v_mfma_f32_16x16x32_bf16 v[10:13], v[176:179], v[216:219], v[10:13]
	v_mfma_f32_16x16x32_bf16 v[2:5], v[184:187], v[216:219], v[2:5]
	v_mfma_f32_16x16x32_bf16 v[58:61], v[180:183], v[196:199], v[58:61]
	v_mfma_f32_16x16x32_bf16 v[50:53], v[188:191], v[196:199], v[50:53]
	v_mfma_f32_16x16x32_bf16 v[42:45], v[180:183], v[204:207], v[42:45]
	v_mfma_f32_16x16x32_bf16 v[34:37], v[188:191], v[204:207], v[34:37]
	v_mfma_f32_16x16x32_bf16 v[26:29], v[180:183], v[212:215], v[26:29]
	v_mfma_f32_16x16x32_bf16 v[18:21], v[188:191], v[212:215], v[18:21]
	v_mfma_f32_16x16x32_bf16 v[10:13], v[180:183], v[220:223], v[10:13]
	v_mfma_f32_16x16x32_bf16 v[2:5], v[188:191], v[220:223], v[2:5]
	s_setprio 0
	s_barrier
	s_cmp_lg_u32 s93, 3
	s_cbranch_scc1 .LS3_n3
	s_mov_b64 s[100:101], 0
	s_bitcmp1_b32 s85, 31
	s_cbranch_scc1 .LD2_B_s
	s_lshr_b32 s98, s85, 16
	s_and_b32 s99, s85, 0xffff
	s_lshr_b32 s100, s99, 2
	s_lshl_b32 s100, s100, 8
	s_and_b32 s99, s99, 3
	s_lshl_b32 s99, s99, 5
	s_add_i32 s100, s100, s99
	s_xor_b32 s99, s98, 0x80
	s_and_b32 s99, s99, 0x80
	s_add_i32 s100, s100, s99
	s_lshl_b32 s100, s100, 13
	s_and_b32 s98, s98, 0x7f
	s_lshl_b32 s98, s98, 6
	s_add_i32 s100, s100, s98
	v_readlane_b32 s98, v244, 6
	v_readlane_b32 s99, v244, 7
	s_nop 3
	s_add_u32 s100, s98, s100
	s_addc_u32 s101, s99, 0
	s_branch .LD2_done_s

; #define PG8_STAGE(bufoff, gbase, voff) do { _Pragma("unroll") for (int _i = 0; _i < 2; ++_i) \
;         __builtin_amdgcn_global_load_lds((const unsigned*)((const char*)(gbase) + (voff)[_i]), (PG8_LAS unsigned*)(lds + (bufoff) + ldsw + _i * 8192), 16, 0, 0); } while (0)
; #define PG8_LDA(dst, b, h) do { _Pragma("unroll") for (int m = 0; m < 4; ++m) _Pragma("unroll") for (int k = 0; k < 2; ++k) dst[m][k] = *(const PG8_LAS bf16x8*)(lds + PG8_SA(b, h) + aoff + m * 2048 + k * 1024); } while (0)
; #define PG8_LDB(dst, b, h) do { _Pragma("unroll") for (int n = 0; n < 2; ++n) _Pragma("unroll") for (int k = 0; k < 2; ++k) dst[n][k] = *(const PG8_LAS bf16x8*)(lds + PG8_SB(b, h) + boff + n * 2048 + k * 1024); } while (0)
; #define PG8_MMA(ai, bj, At, Bt) do { __builtin_amdgcn_s_setprio(3); _Pragma("unroll") for (int m = 0; m < 4; ++m) _Pragma("unroll") for (int n = 0; n < 2; ++n) _Pragma("unroll") for (int k = 0; k < 2; ++k) \
;         acc[ai][bj][m][n] = __builtin_amdgcn_mfma_f32_16x16x32_bf16(Bt[n][k], At[m][k], acc[ai][bj][m][n], 0, 0, 0); __builtin_amdgcn_s_setprio(0); } while (0)
; #define PG8_WAIT_V(n) asm volatile("s_waitcnt vmcnt(" #n ")" ::: "memory")
; #define PG8_WAIT_L(n) asm volatile("s_waitcnt lgkmcnt(" #n ")" ::: "memory")
; #define PG8_BAR __builtin_amdgcn_s_barrier()
; #define PG8_SCHED __builtin_amdgcn_sched_barrier(0)
; template <class Epi, class Sched, bool ALIGN_EPI = false, bool SP2 = false>
; __device__ __forceinline__ void gemm_phase(PG8_LAS unsigned char* lds, const Gemm g, const Sched& S, const Epi& E) {
;     ...
;             PG8_LDB(B0, 1, 0); PG8_LDB(B1, 1, 1); PG8_SCHED; PG8_LDA(At, 1, 0); PG8_STAGE(PG8_SA(0, 1), a2 + hstepA, voffA);
;             PG8_WAIT_V(8); PG8_WAIT_L(0); PG8_BAR; PG8_MMA(0, 0, At, B0); PG8_MMA(0, 1, At, B1); PG8_BAR; PG8_SCHED;
.LS3_n3:
	s_cmp_eq_u64 s[100:101], 0
	s_cbranch_scc1 .LS3_done
	s_cmp_lg_u32 s93, 1
	s_cbranch_scc1 .LS3_n1
	v_mul_f32_e32 v240, v252, v240
	v_mul_f32_e32 v241, v252, v241
	v_mul_f32_e32 v242, v252, v242
	v_mul_f32_e32 v243, v252, v243
	v_cvt_pk_bf16_f32 v240, v240, v241
	v_cvt_pk_bf16_f32 v241, v242, v243
	ds_write2_b32 v255, v240, v241 offset1:1
	s_branch .LS3_done
.LS3_n1:
	s_cmp_lg_u32 s93, 2
	s_cbranch_scc1 .LS3_done
	ds_read_u16 v240, v254 offset:32
	ds_read_u16 v241, v254 offset:100
	ds_read_u16 v242, v254 offset:168
	ds_read_u16 v243, v254 offset:236
.LS3_done:
	s_add_i32 s56, 0, 0x18000
	v_add_u32_e32 v146, s56, v164
	s_add_i32 s57, 0, 0x1c000
	ds_read_b128 v[130:133], v146
	ds_read_b128 v[134:137], v146 offset:1024
	ds_read_b128 v[156:159], v146 offset:2048
	ds_read_b128 v[172:175], v146 offset:3072
	v_add_u32_e32 v146, s57, v164
	ds_read_b128 v[176:179], v146
	ds_read_b128 v[180:183], v146 offset:1024
	ds_read_b128 v[184:187], v146 offset:2048
	ds_read_b128 v[188:191], v146 offset:3072
	s_add_u32 s36, s36, 0x100000
	s_addc_u32 s37, s37, 0
	s_mov_b32 m0, s72
	v_lshl_add_u64 v[230:231], s[36:37], 0, v[138:139]
	ds_read_b128 v[192:195], v169 offset:32768
	ds_read_b128 v[196:199], v169 offset:33792
	ds_read_b128 v[200:203], v169 offset:34816
	ds_read_b128 v[204:207], v169 offset:35840
	ds_read_b128 v[208:211], v169 offset:36864
	ds_read_b128 v[212:215], v169 offset:37888
	ds_read_b128 v[216:219], v169 offset:38912
	ds_read_b128 v[220:223], v169 offset:39936
	global_load_lds_dwordx4 v[230:231], off
	v_lshl_add_u64 v[230:231], s[36:37], 0, v[142:143]
	s_mov_b32 m0, s73
	s_nop 0
	global_load_lds_dwordx4 v[230:231], off
	s_waitcnt vmcnt(8)
	s_waitcnt lgkmcnt(0)
	s_barrier
	s_setprio 3
	s_waitcnt lgkmcnt(0)
	v_mfma_f32_16x16x32_bf16 v[126:129], v[130:133], v[192:195], v[126:129]
	v_mfma_f32_16x16x32_bf16 v[118:121], v[156:159], v[192:195], v[118:121]
	v_mfma_f32_16x16x32_bf16 v[110:113], v[130:133], v[200:203], v[110:113]
	v_mfma_f32_16x16x32_bf16 v[102:105], v[156:159], v[200:203], v[102:105]
	v_mfma_f32_16x16x32_bf16 v[94:97], v[130:133], v[208:211], v[94:97]
	v_mfma_f32_16x16x32_bf16 v[86:89], v[156:159], v[208:211], v[86:89]
	v_mfma_f32_16x16x32_bf16 v[78:81], v[130:133], v[216:219], v[78:81]
	v_mfma_f32_16x16x32_bf16 v[70:73], v[156:159], v[216:219], v[70:73]
	v_mfma_f32_16x16x32_bf16 v[126:129], v[134:137], v[196:199], v[126:129]
	v_mfma_f32_16x16x32_bf16 v[118:121], v[172:175], v[196:199], v[118:121]
	v_mfma_f32_16x16x32_bf16 v[110:113], v[134:137], v[204:207], v[110:113]
	v_mfma_f32_16x16x32_bf16 v[102:105], v[172:175], v[204:207], v[102:105]
	v_mfma_f32_16x16x32_bf16 v[94:97], v[134:137], v[212:215], v[94:97]
	v_mfma_f32_16x16x32_bf16 v[86:89], v[172:175], v[212:215], v[86:89]
	v_mfma_f32_16x16x32_bf16 v[78:81], v[134:137], v[220:223], v[78:81]
	v_mfma_f32_16x16x32_bf16 v[70:73], v[172:175], v[220:223], v[70:73]
	s_setprio 0
	s_setprio 3
	v_mfma_f32_16x16x32_bf16 v[122:125], v[176:179], v[192:195], v[122:125]
	v_mfma_f32_16x16x32_bf16 v[114:117], v[184:187], v[192:195], v[114:117]
	v_mfma_f32_16x16x32_bf16 v[106:109], v[176:179], v[200:203], v[106:109]
	v_mfma_f32_16x16x32_bf16 v[98:101], v[184:187], v[200:203], v[98:101]
	v_mfma_f32_16x16x32_bf16 v[90:93], v[176:179], v[208:211], v[90:93]
	v_mfma_f32_16x16x32_bf16 v[82:85], v[184:187], v[208:211], v[82:85]
	v_mfma_f32_16x16x32_bf16 v[74:77], v[176:179], v[216:219], v[74:77]
	v_mfma_f32_16x16x32_bf16 v[66:69], v[184:187], v[216:219], v[66:69]
	v_mfma_f32_16x16x32_bf16 v[122:125], v[180:183], v[196:199], v[122:125]
	v_mfma_f32_16x16x32_bf16 v[114:117], v[188:191], v[196:199], v[114:117]
	v_mfma_f32_16x16x32_bf16 v[106:109], v[180:183], v[204:207], v[106:109]
	v_mfma_f32_16x16x32_bf16 v[98:101], v[188:191], v[204:207], v[98:101]
	v_mfma_f32_16x16x32_bf16 v[90:93], v[180:183], v[212:215], v[90:93]
	v_mfma_f32_16x16x32_bf16 v[82:85], v[188:191], v[212:215], v[82:85]
	v_mfma_f32_16x16x32_bf16 v[74:77], v[180:183], v[220:223], v[74:77]
	v_mfma_f32_16x16x32_bf16 v[66:69], v[188:191], v[220:223], v[66:69]
	s_setprio 0
	s_barrier
	s_cmp_lg_u32 s93, 3
	s_cbranch_scc1 .LS4_n3
	s_cmp_eq_u64 s[100:101], 0
	s_cbranch_scc1 .LD3_done_s
	s_bitcmp1_b32 s85, 31
	s_cbranch_scc1 .LD3_B_s
	s_lshr_b32 s93, s85, 16
	s_cmp_lt_u32 s93, 0x80
	s_cbranch_scc0 .LD3_gate_s
	v_readlane_b32 s98, v245, 2
	v_readlane_b32 s99, v245, 3
	s_branch .LD3_Am_s

; #define PG8_STAGE(bufoff, gbase, voff) do { _Pragma("unroll") for (int _i = 0; _i < 2; ++_i) \
;         __builtin_amdgcn_global_load_lds((const unsigned*)((const char*)(gbase) + (voff)[_i]), (PG8_LAS unsigned*)(lds + (bufoff) + ldsw + _i * 8192), 16, 0, 0); } while (0)
; #define PG8_LDA(dst, b, h) do { _Pragma("unroll") for (int m = 0; m < 4; ++m) _Pragma("unroll") for (int k = 0; k < 2; ++k) dst[m][k] = *(const PG8_LAS bf16x8*)(lds + PG8_SA(b, h) + aoff + m * 2048 + k * 1024); } while (0)
; #define PG8_MMA(ai, bj, At, Bt) do { __builtin_amdgcn_s_setprio(3); _Pragma("unroll") for (int m = 0; m < 4; ++m) _Pragma("unroll") for (int n = 0; n < 2; ++n) _Pragma("unroll") for (int k = 0; k < 2; ++k) \
;         acc[ai][bj][m][n] = __builtin_amdgcn_mfma_f32_16x16x32_bf16(Bt[n][k], At[m][k], acc[ai][bj][m][n], 0, 0, 0); __builtin_amdgcn_s_setprio(0); } while (0)
; #define PG8_WAIT_V(n) asm volatile("s_waitcnt vmcnt(" #n ")" ::: "memory")
; #define PG8_WAIT_L(n) asm volatile("s_waitcnt lgkmcnt(" #n ")" ::: "memory")
; #define PG8_BAR __builtin_amdgcn_s_barrier()
; #define PG8_SCHED __builtin_amdgcn_sched_barrier(0)
; template <class Epi, class Sched, bool ALIGN_EPI = false, bool SP2 = false>
; __device__ __forceinline__ void gemm_phase(PG8_LAS unsigned char* lds, const Gemm g, const Sched& S, const Epi& E) {
;     ...
;             PG8_LDA(At, 1, 1); PG8_STAGE(PG8_SB(1, 0), b3, voffB); PG8_STAGE(PG8_SB(1, 1), b3 + hstepB, voffB); PG8_STAGE(PG8_SA(1, 0), a3, voffA);
;             PG8_WAIT_V(8); PG8_WAIT_L(0); PG8_BAR; PG8_MMA(1, 0, At, B0); PG8_MMA(1, 1, At, B1); PG8_BAR; PG8_SCHED;
.LS4_n3:
	s_cmp_eq_u64 s[100:101], 0
	s_cbranch_scc1 .LS4_done
	s_cmp_lg_u32 s93, 1
	s_cbranch_scc1 .LS4_n1
	v_mul_f32_e32 v246, v253, v246
	v_mul_f32_e32 v247, v253, v247
	v_mul_f32_e32 v248, v253, v248
	v_mul_f32_e32 v249, v253, v249
	v_cvt_pk_bf16_f32 v246, v246, v247
	v_cvt_pk_bf16_f32 v247, v248, v249
	ds_write2_b32 v255, v246, v247 offset0:136 offset1:137
	s_branch .LS4_done
.LS4_n1:
	s_cmp_lg_u32 s93, 2
	s_cbranch_scc1 .LS4_done
	ds_read_u16 v246, v254 offset:304
	ds_read_u16 v247, v254 offset:372
	ds_read_u16 v248, v254 offset:440
	ds_read_u16 v249, v254 offset:508
.LS4_done:
	s_add_i32 s36, s56, s66
	v_lshl_add_u64 v[160:161], v[160:161], 0, s[18:19]
	s_mov_b32 m0, s36
	ds_read_b128 v[192:195], v169 offset:49152
	ds_read_b128 v[196:199], v169 offset:50176
	ds_read_b128 v[200:203], v169 offset:51200
	ds_read_b128 v[204:207], v169 offset:52224
	ds_read_b128 v[208:211], v169 offset:53248
	ds_read_b128 v[212:215], v169 offset:54272
	ds_read_b128 v[216:219], v169 offset:55296
	ds_read_b128 v[220:223], v169 offset:56320
	global_load_lds_dwordx4 v[160:161], off
	s_add_i32 m0, s36, 0x2000
	s_add_u32 s8, s8, 0x100080
	v_lshl_add_u64 v[160:161], v[224:225], 0, s[18:19]
	s_addc_u32 s9, s9, 0
	s_add_i32 s36, s57, s66
	global_load_lds_dwordx4 v[160:161], off
	v_lshl_add_u64 v[160:161], s[8:9], 0, v[140:141]
	s_mov_b32 m0, s36
	s_nop 0
	global_load_lds_dwordx4 v[160:161], off
	v_lshl_add_u64 v[160:161], s[8:9], 0, v[144:145]
	s_add_i32 m0, s36, 0x2000
	s_nop 0
	global_load_lds_dwordx4 v[160:161], off
	v_lshl_add_u64 v[160:161], v[226:227], 0, s[18:19]
	s_mov_b32 m0, s75
	s_nop 0
	global_load_lds_dwordx4 v[160:161], off
	v_lshl_add_u64 v[160:161], v[228:229], 0, s[18:19]
	s_mov_b32 m0, s76
	s_nop 0
	global_load_lds_dwordx4 v[160:161], off
	s_waitcnt vmcnt(8)
	s_waitcnt lgkmcnt(0)
	s_barrier
	s_setprio 3
	s_waitcnt lgkmcnt(0)
	v_mfma_f32_16x16x32_bf16 v[62:65], v[130:133], v[192:195], v[62:65]
	v_mfma_f32_16x16x32_bf16 v[54:57], v[156:159], v[192:195], v[54:57]
	v_mfma_f32_16x16x32_bf16 v[46:49], v[130:133], v[200:203], v[46:49]
	v_mfma_f32_16x16x32_bf16 v[38:41], v[156:159], v[200:203], v[38:41]
	v_mfma_f32_16x16x32_bf16 v[30:33], v[130:133], v[208:211], v[30:33]
	v_mfma_f32_16x16x32_bf16 v[22:25], v[156:159], v[208:211], v[22:25]
	v_mfma_f32_16x16x32_bf16 v[14:17], v[130:133], v[216:219], v[14:17]
	v_mfma_f32_16x16x32_bf16 v[6:9], v[156:159], v[216:219], v[6:9]
	v_mfma_f32_16x16x32_bf16 v[62:65], v[134:137], v[196:199], v[62:65]
	v_mfma_f32_16x16x32_bf16 v[54:57], v[172:175], v[196:199], v[54:57]
	v_mfma_f32_16x16x32_bf16 v[46:49], v[134:137], v[204:207], v[46:49]
	v_mfma_f32_16x16x32_bf16 v[38:41], v[172:175], v[204:207], v[38:41]
	v_mfma_f32_16x16x32_bf16 v[30:33], v[134:137], v[212:215], v[30:33]
	v_mfma_f32_16x16x32_bf16 v[22:25], v[172:175], v[212:215], v[22:25]
	v_mfma_f32_16x16x32_bf16 v[14:17], v[134:137], v[220:223], v[14:17]
	v_mfma_f32_16x16x32_bf16 v[6:9], v[172:175], v[220:223], v[6:9]
	s_setprio 0
	s_setprio 3
	v_mfma_f32_16x16x32_bf16 v[58:61], v[176:179], v[192:195], v[58:61]
	v_mfma_f32_16x16x32_bf16 v[50:53], v[184:187], v[192:195], v[50:53]
	v_mfma_f32_16x16x32_bf16 v[42:45], v[176:179], v[200:203], v[42:45]
	v_mfma_f32_16x16x32_bf16 v[34:37], v[184:187], v[200:203], v[34:37]
	v_mfma_f32_16x16x32_bf16 v[26:29], v[176:179], v[208:211], v[26:29]
	v_mfma_f32_16x16x32_bf16 v[18:21], v[184:187], v[208:211], v[18:21]
	v_mfma_f32_16x16x32_bf16 v[10:13], v[176:179], v[216:219], v[10:13]
	v_mfma_f32_16x16x32_bf16 v[2:5], v[184:187], v[216:219], v[2:5]
	v_mfma_f32_16x16x32_bf16 v[58:61], v[180:183], v[196:199], v[58:61]
	v_mfma_f32_16x16x32_bf16 v[50:53], v[188:191], v[196:199], v[50:53]
	v_mfma_f32_16x16x32_bf16 v[42:45], v[180:183], v[204:207], v[42:45]
	v_mfma_f32_16x16x32_bf16 v[34:37], v[188:191], v[204:207], v[34:37]
	v_mfma_f32_16x16x32_bf16 v[26:29], v[180:183], v[212:215], v[26:29]
	v_mfma_f32_16x16x32_bf16 v[18:21], v[188:191], v[212:215], v[18:21]
	v_mfma_f32_16x16x32_bf16 v[10:13], v[180:183], v[220:223], v[10:13]
	v_mfma_f32_16x16x32_bf16 v[2:5], v[188:191], v[220:223], v[2:5]
	s_setprio 0
	s_barrier
	s_add_i32 s45, s45, 2
	s_add_u32 s6, s6, 0x100
	s_addc_u32 s7, s7, 0
	s_add_u32 s33, s33, 0x100
	s_addc_u32 s44, s44, 0
	s_cmp_gt_u32 s45, 61
	s_cbranch_scc0 .LBB0_143
	s_and_b64 vcc, exec, s[20:21]
	s_cbranch_vccz .LBB0_148
	s_barrier
	v_lshl_add_u32 v156, s0, 8, v163
	s_cmp_lt_i32 s54, 40
	s_mov_b64 s[0:1], -1
	s_cbranch_scc1 .LBB0_149
